# NSA top-k rounds rewritten: tree argmax per lane, branch-free DPP merge and update (plus v23 changes)
# speedup vs baseline: 1.0126x; 1.0017x over previous
; #define SEL_DPP_STEP(ctrl_) do { const float ov = __uint_as_float((unsigned)__builtin_amdgcn_mov_dpp((int)__float_as_uint(bv), ctrl_, 0xf, 0xf, true)); const int oj = __builtin_amdgcn_mov_dpp(bj, ctrl_, 0xf, 0xf, true); \
;                     if (ov > bv || (ov == bv && oj < bj)) { bv = ov; bj = oj; } } while (0)
; DI void nsa_unit(const bf16* PR, const bf16* VT, const bf16* kcb, const bf16* vctb, bf16* Y, LAS unsigned char* lds, int b, int g, int jt) {
;     ...
;             for (int round = 0; round < 13; ++round) {
;                 float bv = -1.f; int bj = 1 << 20;
; #pragma unroll
;                 for (int k = 0; k < 16; ++k) { if (v[k] > bv) { bv = v[k]; bj = 16 * sub + k; } }
;     ...
;                 SEL_DPP_STEP(0xB1); SEL_DPP_STEP(0x4E); SEL_DPP_STEP(0x141);
;     ...
;                 if ((bj >> 4) == sub) {
; #pragma unroll
;                     for (int k = 0; k < 16; ++k) if (k == (bj & 15)) { v[k] = -1.f; selbits |= 1u << k; }
;                 }
;             }
.LBB0_968:
	v_cmp_gt_f32_e64 s[2:3], v4, v5
	v_cmp_gt_f32_e64 s[4:5], v8, v9
	v_cmp_gt_f32_e64 s[6:7], v12, v13
	v_cmp_gt_f32_e64 s[8:9], v48, v49
	v_cmp_gt_f32_e64 s[10:11], v52, v53
	v_cmp_gt_f32_e64 s[12:13], v59, v60
	v_cmp_gt_f32_e64 s[26:27], v64, v65
	v_cmp_gt_f32_e64 s[28:29], v68, v69
	v_cndmask_b32_e64 v72, v5, v4, s[2:3]
	v_cndmask_b32_e64 v80, v3, v6, s[2:3]
	v_cndmask_b32_e64 v73, v9, v8, s[4:5]
	v_cndmask_b32_e64 v81, v7, v10, s[4:5]
	v_cndmask_b32_e64 v74, v13, v12, s[6:7]
	v_cndmask_b32_e64 v82, v11, v14, s[6:7]
	v_cndmask_b32_e64 v75, v49, v48, s[8:9]
	v_cndmask_b32_e64 v83, v15, v50, s[8:9]
	v_cndmask_b32_e64 v76, v53, v52, s[10:11]
	v_cndmask_b32_e64 v84, v51, v54, s[10:11]
	v_cndmask_b32_e64 v77, v60, v59, s[12:13]
	v_cndmask_b32_e64 v85, v55, v61, s[12:13]
	v_cndmask_b32_e64 v78, v65, v64, s[26:27]
	v_cndmask_b32_e64 v86, v63, v66, s[26:27]
	v_cndmask_b32_e64 v79, v69, v68, s[28:29]
	v_cndmask_b32_e64 v87, v67, v70, s[28:29]
	v_cmp_gt_f32_e64 s[30:31], v73, v72
	v_cmp_gt_f32_e64 s[34:35], v75, v74
	v_cmp_gt_f32_e64 s[36:37], v77, v76
	v_cmp_gt_f32_e64 s[38:39], v79, v78
	v_cndmask_b32_e64 v88, v72, v73, s[30:31]
	v_cndmask_b32_e64 v96, v80, v81, s[30:31]
	v_cndmask_b32_e64 v89, v74, v75, s[34:35]
	v_cndmask_b32_e64 v97, v82, v83, s[34:35]
	v_cndmask_b32_e64 v90, v76, v77, s[36:37]
	v_cndmask_b32_e64 v98, v84, v85, s[36:37]
	v_cndmask_b32_e64 v91, v78, v79, s[38:39]
	v_cndmask_b32_e64 v99, v86, v87, s[38:39]
	v_cmp_gt_f32_e64 s[2:3], v89, v88
	v_cmp_gt_f32_e64 s[4:5], v91, v90
	s_nop 0
	v_cndmask_b32_e64 v100, v88, v89, s[2:3]
	v_cndmask_b32_e64 v102, v96, v97, s[2:3]
	v_cndmask_b32_e64 v101, v90, v91, s[4:5]
	v_cndmask_b32_e64 v103, v98, v99, s[4:5]
	v_cmp_gt_f32_e64 s[2:3], v101, v100
	s_nop 1
	v_cndmask_b32_e64 v58, v100, v101, s[2:3]
	v_cndmask_b32_e64 v57, v102, v103, s[2:3]
	v_cmp_lt_f32_e64 s[4:5], -1.0, v58
	s_nop 1
	v_cndmask_b32_e64 v57, v230, v57, s[4:5]
	s_nop 1
	v_mov_b32_dpp v62, v58 quad_perm:[1,0,3,2] row_mask:0xf bank_mask:0xf bound_ctrl:1
	v_mov_b32_dpp v71, v57 quad_perm:[1,0,3,2] row_mask:0xf bank_mask:0xf bound_ctrl:1
	v_cmp_gt_f32_e64 s[2:3], v62, v58
	v_cmp_eq_f32_e64 s[4:5], v62, v58
	v_cmp_lt_i32_e64 s[6:7], v71, v57
	s_and_b64 s[4:5], s[4:5], s[6:7]
	s_or_b64 s[2:3], s[2:3], s[4:5]
	v_cndmask_b32_e64 v58, v58, v62, s[2:3]
	v_cndmask_b32_e64 v57, v57, v71, s[2:3]
	s_nop 1
	v_mov_b32_dpp v62, v58 quad_perm:[2,3,0,1] row_mask:0xf bank_mask:0xf bound_ctrl:1
	v_mov_b32_dpp v71, v57 quad_perm:[2,3,0,1] row_mask:0xf bank_mask:0xf bound_ctrl:1
	v_cmp_gt_f32_e64 s[2:3], v62, v58
	v_cmp_eq_f32_e64 s[4:5], v62, v58
	v_cmp_lt_i32_e64 s[6:7], v71, v57
	s_and_b64 s[4:5], s[4:5], s[6:7]
	s_or_b64 s[2:3], s[2:3], s[4:5]
	v_cndmask_b32_e64 v58, v58, v62, s[2:3]
	v_cndmask_b32_e64 v57, v57, v71, s[2:3]
	s_nop 1
	v_mov_b32_dpp v62, v58 row_half_mirror row_mask:0xf bank_mask:0xf bound_ctrl:1
	v_mov_b32_dpp v71, v57 row_half_mirror row_mask:0xf bank_mask:0xf bound_ctrl:1
	v_cmp_gt_f32_e64 s[2:3], v62, v58
	v_cmp_eq_f32_e64 s[4:5], v62, v58
	v_cmp_lt_i32_e64 s[6:7], v71, v57
	s_and_b64 s[4:5], s[4:5], s[6:7]
	s_or_b64 s[2:3], s[2:3], s[4:5]
	v_cndmask_b32_e64 v58, v58, v62, s[2:3]
	v_cndmask_b32_e64 v57, v57, v71, s[2:3]
	v_ashrrev_i32_e32 v62, 4, v57
	v_and_b32_e32 v71, 15, v57
	v_cmp_eq_u32_e64 s[2:3], v62, v2
	s_nop 1
	v_cndmask_b32_e64 v71, 16, v71, s[2:3]
	v_cmp_eq_u32_e64 s[2:3], 0, v71
	v_cmp_eq_u32_e64 s[4:5], 1, v71
	v_cmp_eq_u32_e64 s[6:7], 2, v71
	v_cmp_eq_u32_e64 s[8:9], 3, v71
	v_cmp_eq_u32_e64 s[10:11], 4, v71
	v_cmp_eq_u32_e64 s[12:13], 5, v71
	v_cmp_eq_u32_e64 s[26:27], 6, v71
	v_cmp_eq_u32_e64 s[28:29], 7, v71
	v_cmp_eq_u32_e64 s[30:31], 8, v71
	v_cmp_eq_u32_e64 s[34:35], 9, v71
	v_cmp_eq_u32_e64 s[36:37], 10, v71
	v_cmp_eq_u32_e64 s[38:39], 11, v71
	v_cmp_eq_u32_e64 s[40:41], 12, v71
	v_cmp_eq_u32_e64 s[44:45], 13, v71
	v_cmp_eq_u32_e64 s[46:47], 14, v71
	v_cmp_eq_u32_e64 s[48:49], 15, v71
	v_cndmask_b32_e64 v5, v5, -1.0, s[2:3]
	v_cndmask_b32_e64 v4, v4, -1.0, s[4:5]
	v_cndmask_b32_e64 v9, v9, -1.0, s[6:7]
	v_cndmask_b32_e64 v8, v8, -1.0, s[8:9]
	v_cndmask_b32_e64 v13, v13, -1.0, s[10:11]
	v_cndmask_b32_e64 v12, v12, -1.0, s[12:13]
	v_cndmask_b32_e64 v49, v49, -1.0, s[26:27]
	v_cndmask_b32_e64 v48, v48, -1.0, s[28:29]
	v_cndmask_b32_e64 v53, v53, -1.0, s[30:31]
	v_cndmask_b32_e64 v52, v52, -1.0, s[34:35]
	v_cndmask_b32_e64 v60, v60, -1.0, s[36:37]
	v_cndmask_b32_e64 v59, v59, -1.0, s[38:39]
	v_cndmask_b32_e64 v65, v65, -1.0, s[40:41]
	v_cndmask_b32_e64 v64, v64, -1.0, s[44:45]
	v_cndmask_b32_e64 v69, v69, -1.0, s[46:47]
	v_cndmask_b32_e64 v68, v68, -1.0, s[48:49]
	v_lshlrev_b32_e32 v62, v71, v218
	v_and_b32_e32 v62, 0xffff, v62
	v_or_b32_e32 v56, v56, v62
	s_add_i32 s0, s0, -1
	s_cmp_lg_u32 s0, 0
	s_cbranch_scc1 .LBB0_968
